# rows_qk: next row's 17 loads prefetched into a staging register set before computing the current row (cross-row software pipelining)
# speedup vs baseline: 1.0010x; 1.0010x over previous
; __device__ __forceinline__ int TIDX() { int t = threadIdx.x; asm volatile("" : "+v"(t)); return t; }
; __device__ __forceinline__ int BIDX() { int b = blockIdx.x; asm volatile("" : "+s"(b)); return b; }
; __device__ __forceinline__ float bf2f(bf16_t b) { return __uint_as_float(((unsigned)b) << 16); }
;   const int tix = TIDX(), lane = tix & 63, gw = BIDX() * 8 + (tix >> 6), nw = gridDim.x * 8;
;   const bf16_t* qraw = (const bf16_t*)G.out; const bf16_t* knr = (const bf16_t*)(p.ws + O_KNR); const bf16_t* b4 = (const bf16_t*)(p.ws + O_B4);
;   bf16_t* Q = (bf16_t*)(p.ws + O_QK); bf16_t* Kb = Q + (size_t)RGMAX * 1536;
;   const int ri = lane & 31;
;   const float inv = __expf(-(float)(2 * ri) * (1.f / 64.f) * 9.210340371976184f);
;   const float* smn = (const float*)(p.ws + O_SMALL);
;   const float qn0 = smn[S_QN + lane], qn1 = smn[S_QN + 64 + lane], qn2 = smn[S_QN + 128 + lane];
;   const float kn0 = smn[S_KN + lane], kn1 = smn[S_KN + 64 + lane], kn2 = smn[S_KN + 128 + lane];
;   for (int r = gw; r < G.RG; r += nw) {
;     int pos; if (r < NREAL) pos = 16 + (r % G.Ls); else pos = (r - NREAL) & 255;
;     float sn, cs; sincosf((float)pos * inv, &sn, &cs);
;     const float kr = bf2f(b4[(size_t)r * 256 + lane]);
;     for (int h = 0; h < 8; ++h) {
;       { const bf16_t* s = knr + (size_t)r * 1024 + h * 128; float e0 = bf2f(s[lane]), e1 = bf2f(s[64 + lane]), e2 = kr;
.LBB0_417:
	s_andn2_b64 vcc, exec, s[26:27]
	s_cbranch_vccnz .LBB0_481
	s_and_b64 s[0:1], s[88:89], exec
	s_cselect_b32 s51, 2, 1
	s_lshl_b32 s50, s51, 8
	s_bitset1_b32 s50, 14
	s_and_b32 s49, 0xffff, s49
	s_cmp_lt_i32 s49, 4
	s_mov_b64 s[2:3], -1
	s_cbranch_scc1 .LBB0_491
	v_readlane_b32 s42, v254, 27
	s_cmp_lt_i32 s49, 6
	s_mov_b64 s[0:1], -1
	v_readlane_b32 s30, v254, 36
	v_readlane_b32 s43, v254, 28
	v_readlane_b32 s31, v254, 37
	s_cbranch_scc1 .LBB0_483
	s_cmp_gt_i32 s49, 6
	s_brev_b32 s31, 1
	s_movk_i32 s52, 0x1f8
	s_cbranch_scc0 .LBB0_435
	v_mov_b32_e32 v1, v135
	v_readlane_b32 s0, v253, 0
	s_lshl_b32 s0, s0, 3
	v_ashrrev_i32_e32 v4, 6, v1
	v_add_u32_e32 v0, s0, v4
	v_cmp_gt_i32_e32 vcc, s50, v0
	s_and_saveexec_b64 s[2:3], vcc
	s_cbranch_execz .LBB0_434
	v_and_b32_e32 v5, 63, v1
	v_readlane_b32 s24, v253, 19
	v_lshlrev_b32_e32 v132, 2, v5
	v_readlane_b32 s25, v253, 20
	v_cvt_f32_u32_e32 v6, s48
	v_lshlrev_b32_e32 v1, 1, v1
	v_lshl_add_u64 v[2:3], s[24:25], 0, v[132:133]
	v_add_co_u32_e32 v2, vcc, 0x2000, v2
	v_and_b32_e32 v1, 62, v1
	s_nop 0
	v_addc_co_u32_e32 v3, vcc, 0, v3, vcc
	global_load_dword v10, v[2:3], off offset:768
	global_load_dword v11, v[2:3], off offset:1024
	global_load_dword v12, v[2:3], off offset:1280
	v_cvt_f32_ubyte0_e32 v1, v1
	v_mul_f32_e32 v1, 0xbc800000, v1
	v_rcp_iflag_f32_e32 v6, v6
	v_mul_f32_e32 v1, 0x41135d8e, v1
	v_mul_f32_e32 v1, 0x3fb8aa3b, v1
	v_cmp_lt_i32_e32 vcc, v232, v231
	v_exp_f32_e32 v13, v1
	v_mul_f32_e32 v6, 0x4f7ffffe, v6
	v_cndmask_b32_e32 v1, v228, v232, vcc
	v_cmp_lt_i32_e32 vcc, v233, v231
	v_lshlrev_b32_e32 v14, 2, v1
	v_cvt_u32_f32_e32 v6, v6
	v_cndmask_b32_e32 v1, v228, v233, vcc
	v_cmp_lt_i32_e32 vcc, v251, v231
	v_lshlrev_b32_e32 v15, 2, v1
	s_sub_i32 s1, 0, s48
	v_cndmask_b32_e32 v1, v228, v251, vcc
	v_cmp_lt_i32_e32 vcc, v252, v231
	v_lshlrev_b32_e32 v16, 2, v1
	v_lshlrev_b32_e32 v132, 1, v5
	v_cndmask_b32_e32 v1, v228, v252, vcc
	v_cmp_lt_i32_e32 vcc, v236, v231
	v_lshlrev_b32_e32 v17, 2, v1
	v_readlane_b32 s24, v253, 25
	v_cndmask_b32_e32 v1, v228, v236, vcc
	v_cmp_lt_i32_e32 vcc, v237, v231
	v_lshlrev_b32_e32 v18, 2, v1
	v_readlane_b32 s25, v253, 26
	v_cndmask_b32_e32 v1, v228, v237, vcc
	v_lshlrev_b32_e32 v19, 2, v1
	v_mul_lo_u32 v1, s1, v6
	v_cmp_gt_u32_e32 vcc, 32, v5
	v_mul_hi_u32 v1, v6, v1
	v_ashrrev_i32_e32 v5, 31, v4
	s_ashr_i32 s1, s0, 31
	v_add_u32_e32 v20, v6, v1
	v_lshl_add_u64 v[6:7], v[4:5], 0, s[0:1]
	v_lshlrev_b64 v[4:5], 11, v[6:7]
	v_readlane_b32 s0, v254, 23
	v_or_b32_e32 v4, v4, v132
	v_readlane_b32 s1, v254, 24
	v_lshl_add_u64 v[2:3], s[24:25], 0, v[132:133]
	s_mov_b64 s[24:25], 0
	v_lshl_add_u64 v[4:5], s[0:1], 0, v[4:5]
	v_mad_u64_u32 v[8:9], s[0:1], v6, s19, 0
	v_readlane_b32 s0, v254, 25
	v_mad_i32_i24 v7, v7, s19, v9
	v_or_b32_e32 v6, v8, v132
	v_readlane_b32 s1, v254, 26
	s_nop 1
	v_lshl_add_u64 v[6:7], s[0:1], 0, v[6:7]
	v_ashrrev_i32_e32 v99, 31, v0
	v_mov_b32_e32 v98, v0
	v_lshlrev_b64 v[98:99], 9, v[98:99]
	v_lshl_add_u64 v[98:99], v[2:3], 0, v[98:99]
	global_load_ushort v96, v[98:99], off
	global_load_ushort v81, v[4:5], off offset:-128
	global_load_ushort v80, v[4:5], off offset:-256
	global_load_ushort v83, v[4:5], off offset:128
	global_load_ushort v82, v[4:5], off offset:0
	global_load_ushort v85, v[4:5], off offset:384
	global_load_ushort v84, v[4:5], off offset:256
	global_load_ushort v87, v[4:5], off offset:640
	global_load_ushort v86, v[4:5], off offset:512
	global_load_ushort v89, v[4:5], off offset:896
	global_load_ushort v88, v[4:5], off offset:768
	global_load_ushort v91, v[4:5], off offset:1152
	global_load_ushort v90, v[4:5], off offset:1024
	global_load_ushort v93, v[4:5], off offset:1408
	global_load_ushort v92, v[4:5], off offset:1280
	global_load_ushort v95, v[4:5], off offset:1664
	global_load_ushort v94, v[4:5], off offset:1536

; __device__ __forceinline__ float bf2f(bf16_t b) { return __uint_as_float(((unsigned)b) << 16); }
; __device__ __forceinline__ float wave_sum(float v) { for (int o = 32; o >= 1; o >>= 1) v += __shfl_xor(v, o); return v; }
;     ...
;   for (int r = gw; r < G.RG; r += nw) {
;     int pos; if (r < NREAL) pos = 16 + (r % G.Ls); else pos = (r - NREAL) & 255;
;     float sn, cs; sincosf((float)pos * inv, &sn, &cs);
;     const float kr = bf2f(b4[(size_t)r * 256 + lane]);
;     for (int h = 0; h < 8; ++h) {
;       { const bf16_t* s = knr + (size_t)r * 1024 + h * 128; float e0 = bf2f(s[lane]), e1 = bf2f(s[64 + lane]), e2 = kr;
;         float ss = wave_sum(e0 * e0 + e1 * e1 + e2 * e2); const float rs = rsqrtf(ss * (1.f / 192.f) + EPS);
.LBB0_431:
	s_or_b64 exec, exec, s[0:1]
	v_lshlrev_b64 v[24:25], 9, v[0:1]
	v_lshl_add_u64 v[24:25], v[2:3], 0, v[24:25]
	v_mul_f32_e32 v1, v21, v21
	v_fmamk_f32 v25, v1, 0xb94c1982, v226
	v_fmamk_f32 v26, v1, 0x37d75334, v227
	v_fmaak_f32 v25, v1, v25, 0xbe2aaa9d
	v_fmaak_f32 v26, v1, v26, 0x3d2aabf7
	v_lshlrev_b32_e32 v24, 30, v22
	v_and_b32_e32 v22, 1, v22
	v_mul_f32_e32 v25, v1, v25
	v_fmaak_f32 v26, v1, v26, 0xbf000004
	v_fmac_f32_e32 v21, v21, v25
	v_fma_f32 v1, v1, v26, 1.0
	v_cmp_eq_u32_e64 s[0:1], 0, v22
	v_xor_b32_e32 v9, v9, v8
	v_and_b32_e32 v27, 0x80000000, v24
	v_cndmask_b32_e64 v22, v1, v21, s[0:1]
	v_xor_b32_e32 v21, 0x80000000, v21
	v_xor_b32_e32 v9, v9, v22
	v_cndmask_b32_e64 v1, v21, v1, s[0:1]
	v_xor_b32_e32 v9, v9, v27
	v_bitop3_b32 v1, v1, v24, s31 bitop3:0x78
	v_cmp_class_f32_e64 s[0:1], v8, s52
	s_mov_b64 s[26:27], 0
	s_waitcnt vmcnt(0)
	v_mov_b32_e32 v23, v96
	v_mov_b32_e32 v40, v80
	v_mov_b32_e32 v41, v81
	v_mov_b32_e32 v42, v82
	v_mov_b32_e32 v43, v83
	v_mov_b32_e32 v44, v84
	v_mov_b32_e32 v45, v85
	v_mov_b32_e32 v46, v86
	v_mov_b32_e32 v47, v87
	v_mov_b32_e32 v48, v88
	v_mov_b32_e32 v49, v89
	v_mov_b32_e32 v50, v90
	v_mov_b32_e32 v51, v91
	v_mov_b32_e32 v52, v92
	v_mov_b32_e32 v53, v93
	v_mov_b32_e32 v54, v94
	v_mov_b32_e32 v55, v95
	v_add_u32_e32 v97, s30, v0
	v_readlane_b32 s94, v254, 15
	v_readlane_b32 s95, v254, 16
	v_cmp_gt_i32_e64 s[96:97], s50, v97
	v_ashrrev_i32_e32 v99, 31, v97
	v_mov_b32_e32 v98, v97
	v_lshlrev_b64 v[98:99], 9, v[98:99]
	v_lshl_add_u64 v[98:99], v[2:3], 0, v[98:99]
	v_lshl_add_u64 v[100:101], v[4:5], 0, s[94:95]
	s_cmp_eq_u64 s[96:97], 0
	s_cbranch_scc1 .Lqk_nopf
	global_load_ushort v96, v[98:99], off
	global_load_ushort v81, v[100:101], off offset:-128
	global_load_ushort v80, v[100:101], off offset:-256
	global_load_ushort v83, v[100:101], off offset:128
	global_load_ushort v82, v[100:101], off offset:0
	global_load_ushort v85, v[100:101], off offset:384
	global_load_ushort v84, v[100:101], off offset:256
	global_load_ushort v87, v[100:101], off offset:640
	global_load_ushort v86, v[100:101], off offset:512
	global_load_ushort v89, v[100:101], off offset:896
	global_load_ushort v88, v[100:101], off offset:768
	global_load_ushort v91, v[100:101], off offset:1152
	global_load_ushort v90, v[100:101], off offset:1024
	global_load_ushort v93, v[100:101], off offset:1408
	global_load_ushort v92, v[100:101], off offset:1280
	global_load_ushort v95, v[100:101], off offset:1664
	global_load_ushort v94, v[100:101], off offset:1536
.Lqk_nopf:
	v_lshlrev_b32_e32 v22, 16, v23
	v_cndmask_b32_e64 v1, v240, v1, s[0:1]
	v_cndmask_b32_e64 v21, v240, v9, s[0:1]
	v_mul_f32_e32 v23, v22, v22
	v_mov_b64_e32 v[8:9], v[6:7]
	v_lshlrev_b32_e32 v41, 16, v41
	v_lshlrev_b32_e32 v40, 16, v40
	v_lshlrev_b32_e32 v43, 16, v43
	v_lshlrev_b32_e32 v42, 16, v42
	v_lshlrev_b32_e32 v45, 16, v45
	v_lshlrev_b32_e32 v44, 16, v44
	v_lshlrev_b32_e32 v47, 16, v47
	v_lshlrev_b32_e32 v46, 16, v46
	v_lshlrev_b32_e32 v49, 16, v49
	v_lshlrev_b32_e32 v48, 16, v48
	v_lshlrev_b32_e32 v51, 16, v51
	v_lshlrev_b32_e32 v50, 16, v50
	v_lshlrev_b32_e32 v53, 16, v53
	v_lshlrev_b32_e32 v52, 16, v52
	v_lshlrev_b32_e32 v55, 16, v55
	v_lshlrev_b32_e32 v54, 16, v54
	v_mul_f32_e32 v56, v40, v40
	v_mul_f32_e32 v64, v41, v41
	v_mul_f32_e32 v57, v42, v42
	v_mul_f32_e32 v65, v43, v43
	v_mul_f32_e32 v58, v44, v44
	v_mul_f32_e32 v66, v45, v45
	v_mul_f32_e32 v59, v46, v46
	v_mul_f32_e32 v67, v47, v47
	v_mul_f32_e32 v60, v48, v48
	v_mul_f32_e32 v68, v49, v49
	v_mul_f32_e32 v61, v50, v50
	v_mul_f32_e32 v69, v51, v51
	v_mul_f32_e32 v62, v52, v52
	v_mul_f32_e32 v70, v53, v53
	v_mul_f32_e32 v63, v54, v54
	v_mul_f32_e32 v71, v55, v55
	v_add_f32_e32 v56, v56, v64
	v_add_f32_e32 v57, v57, v65
	v_add_f32_e32 v58, v58, v66
	v_add_f32_e32 v59, v59, v67
	v_add_f32_e32 v60, v60, v68
	v_add_f32_e32 v61, v61, v69
	v_add_f32_e32 v62, v62, v70
	v_add_f32_e32 v63, v63, v71
	v_add_f32_e32 v56, v23, v56
	v_add_f32_e32 v57, v23, v57
	v_add_f32_e32 v58, v23, v58
	v_add_f32_e32 v59, v23, v59
	v_add_f32_e32 v60, v23, v60
	v_add_f32_e32 v61, v23, v61
	v_add_f32_e32 v62, v23, v62
	v_add_f32_e32 v63, v23, v63
	ds_bpermute_b32 v64, v14, v56
	ds_bpermute_b32 v65, v14, v57
	ds_bpermute_b32 v66, v14, v58
	ds_bpermute_b32 v67, v14, v59
	ds_bpermute_b32 v68, v14, v60
	ds_bpermute_b32 v69, v14, v61
	ds_bpermute_b32 v70, v14, v62
	ds_bpermute_b32 v71, v14, v63
	s_waitcnt lgkmcnt(0)
	v_add_f32_e32 v56, v56, v64
	v_add_f32_e32 v57, v57, v65
	v_add_f32_e32 v58, v58, v66
	v_add_f32_e32 v59, v59, v67
	v_add_f32_e32 v60, v60, v68
	v_add_f32_e32 v61, v61, v69
	v_add_f32_e32 v62, v62, v70
	v_add_f32_e32 v63, v63, v71
	ds_bpermute_b32 v64, v15, v56
	ds_bpermute_b32 v65, v15, v57
	ds_bpermute_b32 v66, v15, v58
	ds_bpermute_b32 v67, v15, v59
	ds_bpermute_b32 v68, v15, v60
	ds_bpermute_b32 v69, v15, v61
	ds_bpermute_b32 v70, v15, v62
	ds_bpermute_b32 v71, v15, v63
	s_waitcnt lgkmcnt(0)
	v_add_f32_e32 v56, v56, v64
	v_add_f32_e32 v57, v57, v65
	v_add_f32_e32 v58, v58, v66
	v_add_f32_e32 v59, v59, v67
	v_add_f32_e32 v60, v60, v68
	v_add_f32_e32 v61, v61, v69
	v_add_f32_e32 v62, v62, v70
	v_add_f32_e32 v63, v63, v71
	ds_bpermute_b32 v64, v16, v56
	ds_bpermute_b32 v65, v16, v57
	ds_bpermute_b32 v66, v16, v58
	ds_bpermute_b32 v67, v16, v59
	ds_bpermute_b32 v68, v16, v60
	ds_bpermute_b32 v69, v16, v61
	ds_bpermute_b32 v70, v16, v62
	ds_bpermute_b32 v71, v16, v63
	s_waitcnt lgkmcnt(0)
; __device__ __forceinline__ bf16_t f2bf(float f) { return (bf16_t)(cvtpk(f, 0.f) & 0xffffu); }
; __device__ __forceinline__ float bf2f(bf16_t b) { return __uint_as_float(((unsigned)b) << 16); }
; __device__ __forceinline__ float wave_sum(float v) { for (int o = 32; o >= 1; o >>= 1) v += __shfl_xor(v, o); return v; }
;     ...
;       { const bf16_t* s = knr + (size_t)r * 1024 + h * 128; float e0 = bf2f(s[lane]), e1 = bf2f(s[64 + lane]), e2 = kr;
;         float ss = wave_sum(e0 * e0 + e1 * e1 + e2 * e2); const float rs = rsqrtf(ss * (1.f / 192.f) + EPS);
;         e0 *= rs * kn0; e1 *= rs * kn1; e2 *= rs * kn2; const float pr = __shfl_xor(e2, 32);
;         const float o2 = lane < 32 ? e2 * cs - pr * sn : e2 * cs + pr * sn;
;         bf16_t* d = Kb + (size_t)r * 1536 + h * 192; d[lane] = f2bf(e0); d[64 + lane] = f2bf(e1); d[128 + lane] = f2bf(o2); }
	v_add_f32_e32 v56, v56, v64
	v_add_f32_e32 v57, v57, v65
	v_add_f32_e32 v58, v58, v66
	v_add_f32_e32 v59, v59, v67
	v_add_f32_e32 v60, v60, v68
	v_add_f32_e32 v61, v61, v69
	v_add_f32_e32 v62, v62, v70
	v_add_f32_e32 v63, v63, v71
	ds_bpermute_b32 v64, v17, v56
	ds_bpermute_b32 v65, v17, v57
	ds_bpermute_b32 v66, v17, v58
	ds_bpermute_b32 v67, v17, v59
	ds_bpermute_b32 v68, v17, v60
	ds_bpermute_b32 v69, v17, v61
	ds_bpermute_b32 v70, v17, v62
	ds_bpermute_b32 v71, v17, v63
	s_waitcnt lgkmcnt(0)
	v_add_f32_e32 v56, v56, v64
	v_add_f32_e32 v57, v57, v65
	v_add_f32_e32 v58, v58, v66
	v_add_f32_e32 v59, v59, v67
	v_add_f32_e32 v60, v60, v68
	v_add_f32_e32 v61, v61, v69
	v_add_f32_e32 v62, v62, v70
	v_add_f32_e32 v63, v63, v71
	ds_bpermute_b32 v64, v18, v56
	ds_bpermute_b32 v65, v18, v57
	ds_bpermute_b32 v66, v18, v58
	ds_bpermute_b32 v67, v18, v59
	ds_bpermute_b32 v68, v18, v60
	ds_bpermute_b32 v69, v18, v61
	ds_bpermute_b32 v70, v18, v62
	ds_bpermute_b32 v71, v18, v63
	s_waitcnt lgkmcnt(0)
	v_add_f32_e32 v56, v56, v64
	v_add_f32_e32 v57, v57, v65
	v_add_f32_e32 v58, v58, v66
	v_add_f32_e32 v59, v59, v67
	v_add_f32_e32 v60, v60, v68
	v_add_f32_e32 v61, v61, v69
	v_add_f32_e32 v62, v62, v70
	v_add_f32_e32 v63, v63, v71
	ds_bpermute_b32 v64, v19, v56
	ds_bpermute_b32 v65, v19, v57
	ds_bpermute_b32 v66, v19, v58
	ds_bpermute_b32 v67, v19, v59
	ds_bpermute_b32 v68, v19, v60
	ds_bpermute_b32 v69, v19, v61
	ds_bpermute_b32 v70, v19, v62
	ds_bpermute_b32 v71, v19, v63
	s_waitcnt lgkmcnt(0)
	v_add_f32_e32 v56, v56, v64
	v_add_f32_e32 v57, v57, v65
	v_add_f32_e32 v58, v58, v66
	v_add_f32_e32 v59, v59, v67
	v_add_f32_e32 v60, v60, v68
	v_add_f32_e32 v61, v61, v69
	v_add_f32_e32 v62, v62, v70
	v_add_f32_e32 v63, v63, v71
	v_fmamk_f32 v56, v56, 0x3baaaaab, v134
	v_fmamk_f32 v57, v57, 0x3baaaaab, v134
	v_fmamk_f32 v58, v58, 0x3baaaaab, v134
	v_fmamk_f32 v59, v59, 0x3baaaaab, v134
	v_fmamk_f32 v60, v60, 0x3baaaaab, v134
	v_fmamk_f32 v61, v61, 0x3baaaaab, v134
	v_fmamk_f32 v62, v62, 0x3baaaaab, v134
	v_fmamk_f32 v63, v63, 0x3baaaaab, v134
	v_mul_f32_e32 v64, 0x4b800000, v56
	v_mul_f32_e32 v65, 0x4b800000, v57
	v_mul_f32_e32 v66, 0x4b800000, v58
	v_mul_f32_e32 v67, 0x4b800000, v59
	v_mul_f32_e32 v68, 0x4b800000, v60
	v_mul_f32_e32 v69, 0x4b800000, v61
	v_mul_f32_e32 v70, 0x4b800000, v62
	v_mul_f32_e32 v71, 0x4b800000, v63
	v_cmp_gt_f32_e64 s[28:29], s93, v56
	v_cmp_gt_f32_e64 s[68:69], s93, v57
	v_cmp_gt_f32_e64 s[70:71], s93, v58
	v_cmp_gt_f32_e64 s[72:73], s93, v59
	v_cmp_gt_f32_e64 s[76:77], s93, v60
	v_cmp_gt_f32_e64 s[78:79], s93, v61
	v_cmp_gt_f32_e64 s[84:85], s93, v62
	v_cmp_gt_f32_e64 s[86:87], s93, v63
	v_cndmask_b32_e64 v56, v56, v64, s[28:29]
	v_cndmask_b32_e64 v57, v57, v65, s[68:69]
	v_cndmask_b32_e64 v58, v58, v66, s[70:71]
	v_cndmask_b32_e64 v59, v59, v67, s[72:73]
	v_cndmask_b32_e64 v60, v60, v68, s[76:77]
	v_cndmask_b32_e64 v61, v61, v69, s[78:79]
	v_cndmask_b32_e64 v62, v62, v70, s[84:85]
	v_cndmask_b32_e64 v63, v63, v71, s[86:87]
	v_rsq_f32_e32 v56, v56
	v_rsq_f32_e32 v57, v57
	v_rsq_f32_e32 v58, v58
	v_rsq_f32_e32 v59, v59
	v_rsq_f32_e32 v60, v60
	v_rsq_f32_e32 v61, v61
	v_rsq_f32_e32 v62, v62
	v_rsq_f32_e32 v63, v63
	v_mul_f32_e32 v64, 0x45800000, v56
	v_mul_f32_e32 v65, 0x45800000, v57
	v_mul_f32_e32 v66, 0x45800000, v58
	v_mul_f32_e32 v67, 0x45800000, v59
	v_mul_f32_e32 v68, 0x45800000, v60
	v_mul_f32_e32 v69, 0x45800000, v61
	v_mul_f32_e32 v70, 0x45800000, v62
	v_mul_f32_e32 v71, 0x45800000, v63
	v_cndmask_b32_e64 v56, v56, v64, s[28:29]
	v_cndmask_b32_e64 v57, v57, v65, s[68:69]
	v_cndmask_b32_e64 v58, v58, v66, s[70:71]
	v_cndmask_b32_e64 v59, v59, v67, s[72:73]
	v_cndmask_b32_e64 v60, v60, v68, s[76:77]
	v_cndmask_b32_e64 v61, v61, v69, s[78:79]
	v_cndmask_b32_e64 v62, v62, v70, s[84:85]
	v_cndmask_b32_e64 v63, v63, v71, s[86:87]
	v_mul_f32_e32 v64, v12, v56
	v_mul_f32_e32 v65, v12, v57
	v_mul_f32_e32 v66, v12, v58
	v_mul_f32_e32 v67, v12, v59
	v_mul_f32_e32 v68, v12, v60
	v_mul_f32_e32 v69, v12, v61
	v_mul_f32_e32 v70, v12, v62
	v_mul_f32_e32 v71, v12, v63
	v_mul_f32_e32 v64, v64, v22
	v_mul_f32_e32 v65, v65, v22
	v_mul_f32_e32 v66, v66, v22
	v_mul_f32_e32 v67, v67, v22
	v_mul_f32_e32 v68, v68, v22
	v_mul_f32_e32 v69, v69, v22
	v_mul_f32_e32 v70, v70, v22
	v_mul_f32_e32 v71, v71, v22
	ds_bpermute_b32 v72, v14, v64
	ds_bpermute_b32 v73, v14, v65
	ds_bpermute_b32 v74, v14, v66
	ds_bpermute_b32 v75, v14, v67
	ds_bpermute_b32 v76, v14, v68
	ds_bpermute_b32 v77, v14, v69
	ds_bpermute_b32 v78, v14, v70
	ds_bpermute_b32 v79, v14, v71
	v_mul_f32_e32 v36, v10, v56
	v_mul_f32_e32 v37, v11, v56
	v_mul_f32_e32 v40, v36, v40
	v_mul_f32_e32 v41, v37, v41
	v_cvt_pk_bf16_f32 v40, v40, s0
	v_cvt_pk_bf16_f32 v41, v41, s0
	global_store_short v[8:9], v40, off offset:-384
	global_store_short v[8:9], v41, off offset:-256
	v_mul_f32_e32 v36, v10, v57
	v_mul_f32_e32 v37, v11, v57
	v_mul_f32_e32 v42, v36, v42
	v_mul_f32_e32 v43, v37, v43
	v_cvt_pk_bf16_f32 v42, v42, s0
	v_cvt_pk_bf16_f32 v43, v43, s0
	global_store_short v[8:9], v42, off offset:0
	global_store_short v[8:9], v43, off offset:128
	v_mul_f32_e32 v36, v10, v58
	v_mul_f32_e32 v37, v11, v58
	v_mul_f32_e32 v44, v36, v44
	v_mul_f32_e32 v45, v37, v45
	v_cvt_pk_bf16_f32 v44, v44, s0
	v_cvt_pk_bf16_f32 v45, v45, s0
	global_store_short v[8:9], v44, off offset:384
	global_store_short v[8:9], v45, off offset:512
	v_mul_f32_e32 v36, v10, v59
	v_mul_f32_e32 v37, v11, v59
	v_mul_f32_e32 v46, v36, v46
	v_mul_f32_e32 v47, v37, v47
	v_cvt_pk_bf16_f32 v46, v46, s0
	v_cvt_pk_bf16_f32 v47, v47, s0
	global_store_short v[8:9], v46, off offset:768
	global_store_short v[8:9], v47, off offset:896
	v_mul_f32_e32 v36, v10, v60
	v_mul_f32_e32 v37, v11, v60
	v_mul_f32_e32 v48, v36, v48
	v_mul_f32_e32 v49, v37, v49
	v_cvt_pk_bf16_f32 v48, v48, s0
	v_cvt_pk_bf16_f32 v49, v49, s0
	global_store_short v[8:9], v48, off offset:1152
	global_store_short v[8:9], v49, off offset:1280
	v_mul_f32_e32 v36, v10, v61
	v_mul_f32_e32 v37, v11, v61
	v_mul_f32_e32 v50, v36, v50
	v_mul_f32_e32 v51, v37, v51
	v_cvt_pk_bf16_f32 v50, v50, s0
	v_cvt_pk_bf16_f32 v51, v51, s0
	global_store_short v[8:9], v50, off offset:1536
	global_store_short v[8:9], v51, off offset:1664
	v_mul_f32_e32 v36, v10, v62
	v_mul_f32_e32 v37, v11, v62
	v_mul_f32_e32 v52, v36, v52
	v_mul_f32_e32 v53, v37, v53
	v_cvt_pk_bf16_f32 v52, v52, s0
	v_cvt_pk_bf16_f32 v53, v53, s0
	global_store_short v[8:9], v52, off offset:1920
	global_store_short v[8:9], v53, off offset:2048
	v_mul_f32_e32 v36, v10, v63
	v_mul_f32_e32 v37, v11, v63
	v_mul_f32_e32 v54, v36, v54
	v_mul_f32_e32 v55, v37, v55
	v_cvt_pk_bf16_f32 v54, v54, s0
	v_cvt_pk_bf16_f32 v55, v55, s0
	global_store_short v[8:9], v54, off offset:2304
	global_store_short v[8:9], v55, off offset:2432
	s_waitcnt lgkmcnt(0)
; __device__ __forceinline__ bf16_t f2bf(float f) { return (bf16_t)(cvtpk(f, 0.f) & 0xffffu); }
; __device__ __forceinline__ float bf2f(bf16_t b) { return __uint_as_float(((unsigned)b) << 16); }
; __device__ __forceinline__ float wave_sum(float v) { for (int o = 32; o >= 1; o >>= 1) v += __shfl_xor(v, o); return v; }
;     ...
;   for (int r = gw; r < G.RG; r += nw) {
;     int pos; if (r < NREAL) pos = 16 + (r % G.Ls); else pos = (r - NREAL) & 255;
;     float sn, cs; sincosf((float)pos * inv, &sn, &cs);
;     const float kr = bf2f(b4[(size_t)r * 256 + lane]);
;     for (int h = 0; h < 8; ++h) {
;       { const bf16_t* s = knr + (size_t)r * 1024 + h * 128; float e0 = bf2f(s[lane]), e1 = bf2f(s[64 + lane]), e2 = kr;
;         float ss = wave_sum(e0 * e0 + e1 * e1 + e2 * e2); const float rs = rsqrtf(ss * (1.f / 192.f) + EPS);
;         e0 *= rs * kn0; e1 *= rs * kn1; e2 *= rs * kn2; const float pr = __shfl_xor(e2, 32);
;         const float o2 = lane < 32 ? e2 * cs - pr * sn : e2 * cs + pr * sn;
;         bf16_t* d = Kb + (size_t)r * 1536 + h * 192; d[lane] = f2bf(e0); d[64 + lane] = f2bf(e1); d[128 + lane] = f2bf(o2); }
	v_mul_f32_e32 v72, v21, v72
	v_mul_f32_e32 v73, v21, v73
	v_mul_f32_e32 v74, v21, v74
	v_mul_f32_e32 v75, v21, v75
	v_mul_f32_e32 v76, v21, v76
	v_mul_f32_e32 v77, v21, v77
	v_mul_f32_e32 v78, v21, v78
	v_mul_f32_e32 v79, v21, v79
	v_cndmask_b32_e64 v72, v72, -v72, vcc
	v_cndmask_b32_e64 v73, v73, -v73, vcc
	v_cndmask_b32_e64 v74, v74, -v74, vcc
	v_cndmask_b32_e64 v75, v75, -v75, vcc
	v_cndmask_b32_e64 v76, v76, -v76, vcc
	v_cndmask_b32_e64 v77, v77, -v77, vcc
	v_cndmask_b32_e64 v78, v78, -v78, vcc
	v_cndmask_b32_e64 v79, v79, -v79, vcc
	v_fmac_f32_e32 v72, v1, v64
	v_fmac_f32_e32 v73, v1, v65
	v_fmac_f32_e32 v74, v1, v66
	v_fmac_f32_e32 v75, v1, v67
	v_fmac_f32_e32 v76, v1, v68
	v_fmac_f32_e32 v77, v1, v69
	v_fmac_f32_e32 v78, v1, v70
	v_fmac_f32_e32 v79, v1, v71
	v_cvt_pk_bf16_f32 v72, v72, s0
	global_store_short v[8:9], v72, off offset:-128
	v_cvt_pk_bf16_f32 v73, v73, s0
	global_store_short v[8:9], v73, off offset:256
	v_cvt_pk_bf16_f32 v74, v74, s0
	global_store_short v[8:9], v74, off offset:640
	v_cvt_pk_bf16_f32 v75, v75, s0
	global_store_short v[8:9], v75, off offset:1024
	v_cvt_pk_bf16_f32 v76, v76, s0
	global_store_short v[8:9], v76, off offset:1408
	v_cvt_pk_bf16_f32 v77, v77, s0
	global_store_short v[8:9], v77, off offset:1792
	v_cvt_pk_bf16_f32 v78, v78, s0
	global_store_short v[8:9], v78, off offset:2176
	v_cvt_pk_bf16_f32 v79, v79, s0
	global_store_short v[8:9], v79, off offset:2560
	s_movk_i32 s26, 0x800
	s_cmpk_eq_i32 s26, 0x800
	v_readlane_b32 s0, v254, 15
	v_add_u32_e32 v0, s30, v0
	v_readlane_b32 s1, v254, 16
	v_lshl_add_u64 v[6:7], v[6:7], 0, s[42:43]
	s_nop 0
	v_lshl_add_u64 v[4:5], v[4:5], 0, s[0:1]
	v_cmp_le_i32_e64 s[0:1], s50, v0
	s_or_b64 s[24:25], s[0:1], s[24:25]
	s_andn2_b64 exec, exec, s[24:25]
	s_cbranch_execnz .LBB0_423
